# speedup vs baseline: 1.1246x; 1.0082x over previous
; DEV void phase_ml_in(const Params& p, unsigned char* smem) {
;     ...
;   for (int t = blockIdx.x; t < ntile; t += gridDim.x) {
;     int nt = t % 25, mt = t / 25;
;     const bf16_t* A = p.hbuf + (size_t)mt * 128 * 1024;
;     if (nt < 8 || (nt >= 16 && nt < 24)) {
;       bf16_t* obase = nt < 8 ? p.qb : p.ob - 2048;
.LBB0_845:
	s_and_b32 s0, s57, 7
	s_mul_i32 s1, s0, 0x19c
	s_min_u32 s0, s0, 4
	s_add_i32 s1, s1, s0
	s_lshr_b32 s0, s57, 3
	s_add_i32 s22, s1, s0
	s_cmpk_lt_u32 s22, 0xc80
	s_cbranch_scc0 .Lmlin_tail_grp
	s_lshr_b32 s0, s22, 3
	s_mul_hi_i32 s0, s0, 0x51eb851f
	s_ashr_i32 s0, s0, 3
	s_mul_i32 s1, s0, 0xc8
	s_sub_i32 s1, s22, s1
	s_lshl_b32 s20, s0, 3
	s_and_b32 s0, s1, 7
	s_add_i32 s20, s20, s0
	s_lshr_b32 s22, s1, 3
	s_branch .Lmlin_grp_done
.Lmlin_tail_grp:
	s_sub_i32 s1, s22, 0xc80
	s_and_b32 s0, s1, 3
	s_add_i32 s20, s0, 0x80
	s_lshr_b32 s22, s1, 2
.Lmlin_grp_done:
	s_ashr_i32 s21, s20, 31
	s_lshl_b64 s[0:1], s[20:21], 18
	s_add_u32 s30, s46, s0
	s_addc_u32 s31, s47, s1
	s_cmp_lt_i32 s22, 8
	s_cselect_b64 s[28:29], -1, 0
	s_cmp_gt_i32 s22, 7
	s_cselect_b64 s[0:1], -1, 0
	s_and_b32 s2, s22, 0x7ffffff8
	s_cmp_lg_u32 s2, 16
	s_cselect_b64 s[2:3], -1, 0
	s_and_b64 s[2:3], s[0:1], s[2:3]
	s_mov_b64 s[0:1], -1
	s_and_b64 vcc, exec, s[2:3]
	s_cbranch_vccnz .LBB0_847
	s_and_b64 vcc, exec, s[0:1]
	s_cbranch_vccz .LBB0_844
	s_branch .LBB0_1639
